# as v7 plus nt on write-once f32 output stores (final norm, scan states)
# baseline (speedup 1.0000x reference)
.LBB0_1092:
	s_waitcnt vmcnt(0)
	v_lshl_add_u64 v[20:21], s[54:55], 2, v[60:61]
	v_mov_b32_e32 v16, v26
	v_mov_b32_e32 v17, v2
	v_mov_b32_e32 v18, v8
	v_mov_b32_e32 v19, v6
	v_mov_b32_e32 v24, v27
	v_mov_b32_e32 v26, v9
	v_mov_b32_e32 v27, v7
	v_mov_b32_e32 v6, v12
	v_mov_b32_e32 v7, v10
	v_mov_b32_e32 v8, v4
	v_mov_b32_e32 v9, v14
	v_mov_b32_e32 v2, v13
	v_mov_b32_e32 v4, v5
	v_mov_b32_e32 v5, v15
	global_store_dwordx4 v[20:21], v[16:19], off nt
	global_store_dwordx4 v[20:21], v[24:27], off offset:256 nt
	global_store_dwordx4 v[20:21], v[6:9], off offset:16 nt
	global_store_dwordx4 v[20:21], v[2:5], off offset:272 nt
	s_branch .LBB0_1067

.LBB0_1180:
	s_ashr_i32 s41, s40, 31
	s_lshl_b64 s[14:15], s[40:41], 14
	v_lshl_add_u64 v[6:7], v[78:79], 0, s[14:15]
	v_mov_b32_e32 v2, v18
	v_mov_b32_e32 v3, v20
	v_mov_b32_e32 v4, v22
	v_mov_b32_e32 v5, v24
	global_store_dwordx4 v[6:7], v[2:5], off nt
	v_mov_b32_e32 v20, v19
	v_mov_b32_e32 v22, v23
	v_mov_b32_e32 v23, v25
	v_mov_b32_e32 v2, v26
	v_mov_b32_e32 v3, v28
	v_mov_b32_e32 v4, v30
	v_mov_b32_e32 v5, v32
	v_mov_b32_e32 v28, v27
	v_mov_b32_e32 v30, v31
	v_mov_b32_e32 v31, v33
	global_store_dwordx4 v[6:7], v[20:23], off offset:256 nt
	global_store_dwordx4 v[6:7], v[2:5], off offset:16 nt
	global_store_dwordx4 v[6:7], v[28:31], off offset:272 nt
	s_branch .LBB0_1147

.LBB0_1852:
	v_lshl_add_u64 v[2:3], s[34:35], 0, v[30:31]
	global_load_dwordx4 v[46:49], v[16:17], off offset:16
	global_load_dwordx4 v[50:53], v[16:17], off
	global_load_dword v36, v[2:3], off
	v_lshl_add_u64 v[0:1], s[34:35], 0, v[32:33]
	v_add_co_u32_e32 v70, vcc, 0x30c00000, v0
	s_add_i32 s15, s15, s94
	s_nop 0
	v_addc_co_u32_e32 v71, vcc, 0, v1, vcc
	global_load_dwordx4 v[54:57], v[70:71], off
	global_load_dwordx4 v[58:61], v[70:71], off offset:1024
	global_load_dwordx4 v[62:65], v[70:71], off offset:2048
	v_add_co_u32_e32 v72, vcc, s13, v0
	v_lshl_add_u64 v[30:31], v[30:31], 0, s[0:1]
	s_nop 0
	v_addc_co_u32_e32 v73, vcc, 0, v1, vcc
	global_load_dwordx4 v[66:69], v[70:71], off offset:3072
	global_load_dwordx4 v[12:15], v[72:73], off
	global_load_dwordx4 v[8:11], v[72:73], off offset:1024
	global_load_dwordx4 v[4:7], v[72:73], off offset:2048
	global_load_dwordx4 v[0:3], v[72:73], off offset:3072
	v_lshl_add_u64 v[32:33], v[32:33], 0, s[4:5]
	s_cmpk_lt_i32 s15, 0x2000
	s_waitcnt vmcnt(8)
	ds_bpermute_b32 v45, v37, v36
	s_waitcnt vmcnt(7)
	v_lshlrev_b32_e32 v70, 16, v54
	s_waitcnt lgkmcnt(0)
	v_add_f32_e32 v36, v36, v45
	ds_bpermute_b32 v45, v38, v36
	v_and_b32_e32 v71, 0xffff0000, v54
	v_lshlrev_b32_e32 v54, 16, v55
	v_and_b32_e32 v55, 0xffff0000, v55
	v_lshlrev_b32_e32 v72, 16, v56
	s_waitcnt lgkmcnt(0)
	v_add_f32_e32 v36, v36, v45
	ds_bpermute_b32 v45, v39, v36
	v_and_b32_e32 v73, 0xffff0000, v56
	v_lshlrev_b32_e32 v56, 16, v57
	v_and_b32_e32 v57, 0xffff0000, v57
	s_waitcnt lgkmcnt(0)
	v_add_f32_e32 v36, v36, v45
	ds_bpermute_b32 v45, v40, v36
	s_waitcnt lgkmcnt(0)
	v_add_f32_e32 v36, v36, v45
	ds_bpermute_b32 v45, v41, v36
	s_waitcnt lgkmcnt(0)
	v_add_f32_e32 v36, v36, v45
	ds_bpermute_b32 v45, v42, v36
	s_waitcnt lgkmcnt(0)
	v_add_f32_e32 v36, v36, v45
	v_fmamk_f32 v36, v36, 0x39800000, v43
	v_mul_f32_e32 v45, 0x4f800000, v36
	v_cmp_gt_f32_e32 vcc, s14, v36
	s_nop 1
	v_cndmask_b32_e32 v36, v36, v45, vcc
	v_sqrt_f32_e32 v45, v36
	s_nop 0
	v_add_u32_e32 v74, -1, v45
	v_add_u32_e32 v75, 1, v45
	v_fma_f32 v76, -v74, v45, v36
	v_fma_f32 v77, -v75, v45, v36
	v_cmp_ge_f32_e64 s[2:3], 0, v76
	s_nop 1
	v_cndmask_b32_e64 v45, v45, v74, s[2:3]
	v_cmp_lt_f32_e64 s[2:3], 0, v77
	s_nop 1
	v_cndmask_b32_e64 v45, v45, v75, s[2:3]
	v_mul_f32_e32 v74, 0x37800000, v45
	v_cndmask_b32_e32 v45, v45, v74, vcc
	v_cmp_class_f32_e32 vcc, v36, v44
	s_nop 1
	v_cndmask_b32_e32 v36, v45, v36, vcc
	v_div_scale_f32 v45, s[2:3], v36, v36, 1.0
	v_rcp_f32_e32 v75, v45
	v_div_scale_f32 v74, vcc, 1.0, v36, 1.0
	v_fma_f32 v76, -v45, v75, 1.0
	v_fmac_f32_e32 v75, v76, v75
	v_mul_f32_e32 v76, v74, v75
	v_fma_f32 v77, -v45, v76, v74
	v_fmac_f32_e32 v76, v77, v75
	v_fma_f32 v45, -v45, v76, v74
	v_div_fmas_f32 v45, v45, v75, v76
	v_div_fixup_f32 v36, v45, v36, 1.0
	v_pk_mul_f32 v[70:71], v[36:37], v[70:71] op_sel_hi:[0,1]
	v_pk_mul_f32 v[54:55], v[36:37], v[54:55] op_sel_hi:[0,1]
	v_pk_mul_f32 v[72:73], v[36:37], v[72:73] op_sel_hi:[0,1]
	v_pk_mul_f32 v[56:57], v[36:37], v[56:57] op_sel_hi:[0,1]
	v_pk_mul_f32 v[52:53], v[52:53], v[54:55]
	v_pk_mul_f32 v[50:51], v[50:51], v[70:71]
	v_pk_mul_f32 v[48:49], v[48:49], v[56:57]
	v_pk_mul_f32 v[46:47], v[46:47], v[72:73]
	global_store_dwordx4 v[34:35], v[50:53], off nt
	global_store_dwordx4 v[34:35], v[46:49], off offset:16 nt
	global_load_dwordx4 v[46:49], v[16:17], off offset:2048
	s_nop 0
	global_load_dwordx4 v[50:53], v[16:17], off offset:2064
	s_waitcnt vmcnt(10)
	v_lshlrev_b32_e32 v54, 16, v58
	v_and_b32_e32 v55, 0xffff0000, v58
	v_lshlrev_b32_e32 v56, 16, v59
	v_and_b32_e32 v57, 0xffff0000, v59
	v_lshlrev_b32_e32 v58, 16, v60
	v_and_b32_e32 v59, 0xffff0000, v60
	v_lshlrev_b32_e32 v60, 16, v61
	v_and_b32_e32 v61, 0xffff0000, v61
	v_pk_mul_f32 v[56:57], v[36:37], v[56:57] op_sel_hi:[0,1]
	v_pk_mul_f32 v[54:55], v[36:37], v[54:55] op_sel_hi:[0,1]
	v_pk_mul_f32 v[60:61], v[36:37], v[60:61] op_sel_hi:[0,1]
	v_pk_mul_f32 v[58:59], v[36:37], v[58:59] op_sel_hi:[0,1]
	s_waitcnt vmcnt(1)
	v_pk_mul_f32 v[46:47], v[46:47], v[54:55]
	v_pk_mul_f32 v[48:49], v[48:49], v[56:57]
	s_waitcnt vmcnt(0)
	v_pk_mul_f32 v[50:51], v[50:51], v[58:59]
	v_pk_mul_f32 v[52:53], v[52:53], v[60:61]
	global_store_dwordx4 v[34:35], v[46:49], off offset:2048 nt
	global_store_dwordx4 v[34:35], v[50:53], off offset:2064 nt
	global_load_dwordx4 v[46:49], v[18:19], off
	s_nop 0
	global_load_dwordx4 v[50:53], v[18:19], off offset:16
	v_add_co_u32_e32 v54, vcc, s10, v34
	v_lshlrev_b32_e32 v58, 16, v62
	s_nop 0
	v_addc_co_u32_e32 v55, vcc, 0, v35, vcc
	v_and_b32_e32 v59, 0xffff0000, v62
	v_lshlrev_b32_e32 v60, 16, v63
	v_and_b32_e32 v61, 0xffff0000, v63
	v_add_co_u32_e32 v56, vcc, s11, v34
	v_lshlrev_b32_e32 v62, 16, v64
	v_and_b32_e32 v63, 0xffff0000, v64
	v_lshlrev_b32_e32 v64, 16, v65
	v_and_b32_e32 v65, 0xffff0000, v65
	v_pk_mul_f32 v[60:61], v[36:37], v[60:61] op_sel_hi:[0,1]
	v_pk_mul_f32 v[58:59], v[36:37], v[58:59] op_sel_hi:[0,1]
	v_addc_co_u32_e32 v57, vcc, 0, v35, vcc
	v_pk_mul_f32 v[64:65], v[36:37], v[64:65] op_sel_hi:[0,1]
	v_pk_mul_f32 v[62:63], v[36:37], v[62:63] op_sel_hi:[0,1]
	s_waitcnt vmcnt(1)
	v_pk_mul_f32 v[46:47], v[58:59], v[46:47]
	v_pk_mul_f32 v[48:49], v[60:61], v[48:49]
	s_waitcnt vmcnt(0)
	v_pk_mul_f32 v[50:51], v[62:63], v[50:51]
	v_pk_mul_f32 v[52:53], v[64:65], v[52:53]
	global_store_dwordx4 v[56:57], v[46:49], off offset:-4096 nt
	global_store_dwordx4 v[54:55], v[50:53], off offset:16 nt
	global_load_dwordx4 v[46:49], v[20:21], off
	s_nop 0
	global_load_dwordx4 v[50:53], v[20:21], off offset:16
	v_lshlrev_b32_e32 v58, 16, v66
	v_and_b32_e32 v59, 0xffff0000, v66
	v_lshlrev_b32_e32 v60, 16, v67
	v_and_b32_e32 v61, 0xffff0000, v67
	v_lshlrev_b32_e32 v62, 16, v68
	v_and_b32_e32 v63, 0xffff0000, v68
	v_lshlrev_b32_e32 v64, 16, v69
	v_and_b32_e32 v65, 0xffff0000, v69
	v_pk_mul_f32 v[60:61], v[36:37], v[60:61] op_sel_hi:[0,1]
	v_pk_mul_f32 v[58:59], v[36:37], v[58:59] op_sel_hi:[0,1]
	v_pk_mul_f32 v[64:65], v[36:37], v[64:65] op_sel_hi:[0,1]
	v_pk_mul_f32 v[62:63], v[36:37], v[62:63] op_sel_hi:[0,1]
	s_waitcnt vmcnt(1)
	v_pk_mul_f32 v[46:47], v[58:59], v[46:47]
	v_pk_mul_f32 v[48:49], v[60:61], v[48:49]
	s_waitcnt vmcnt(0)
	v_pk_mul_f32 v[50:51], v[62:63], v[50:51]
	v_pk_mul_f32 v[52:53], v[64:65], v[52:53]
	global_store_dwordx4 v[54:55], v[46:49], off offset:2048 nt
	global_store_dwordx4 v[54:55], v[50:53], off offset:2064 nt
	global_load_dwordx4 v[46:49], v[22:23], off
	s_nop 0
	global_load_dwordx4 v[50:53], v[22:23], off offset:16
	v_lshlrev_b32_e32 v54, 16, v12
	v_and_b32_e32 v55, 0xffff0000, v12
	v_lshlrev_b32_e32 v12, 16, v13
	v_and_b32_e32 v13, 0xffff0000, v13
	v_lshlrev_b32_e32 v58, 16, v14
	v_and_b32_e32 v59, 0xffff0000, v14
	v_lshlrev_b32_e32 v14, 16, v15
	v_and_b32_e32 v15, 0xffff0000, v15
	v_pk_mul_f32 v[60:61], v[36:37], v[12:13] op_sel_hi:[0,1]
	v_pk_mul_f32 v[12:13], v[36:37], v[54:55] op_sel_hi:[0,1]
	v_pk_mul_f32 v[54:55], v[36:37], v[14:15] op_sel_hi:[0,1]
	v_pk_mul_f32 v[58:59], v[36:37], v[58:59] op_sel_hi:[0,1]
	s_waitcnt vmcnt(1)
	v_pk_mul_f32 v[12:13], v[12:13], v[46:47]
	v_pk_mul_f32 v[14:15], v[60:61], v[48:49]
	s_waitcnt vmcnt(0)
	v_pk_mul_f32 v[46:47], v[58:59], v[50:51]
	v_pk_mul_f32 v[48:49], v[54:55], v[52:53]
	global_store_dwordx4 v[56:57], v[12:15], off nt
	global_store_dwordx4 v[56:57], v[46:49], off offset:16 nt
	global_load_dwordx4 v[12:15], v[24:25], off
	s_nop 0
	global_load_dwordx4 v[46:49], v[24:25], off offset:16
	v_lshlrev_b32_e32 v50, 16, v8
	v_and_b32_e32 v51, 0xffff0000, v8
	v_lshlrev_b32_e32 v8, 16, v9
	v_and_b32_e32 v9, 0xffff0000, v9
	v_lshlrev_b32_e32 v52, 16, v10
	v_and_b32_e32 v53, 0xffff0000, v10
	v_lshlrev_b32_e32 v10, 16, v11
	v_and_b32_e32 v11, 0xffff0000, v11
	v_pk_mul_f32 v[54:55], v[36:37], v[8:9] op_sel_hi:[0,1]
	v_pk_mul_f32 v[8:9], v[36:37], v[50:51] op_sel_hi:[0,1]
	v_pk_mul_f32 v[50:51], v[36:37], v[10:11] op_sel_hi:[0,1]
	v_pk_mul_f32 v[52:53], v[36:37], v[52:53] op_sel_hi:[0,1]
	s_waitcnt vmcnt(1)
	v_pk_mul_f32 v[8:9], v[8:9], v[12:13]
	v_pk_mul_f32 v[10:11], v[54:55], v[14:15]
	s_waitcnt vmcnt(0)
	v_pk_mul_f32 v[12:13], v[52:53], v[46:47]
	v_pk_mul_f32 v[14:15], v[50:51], v[48:49]
	global_store_dwordx4 v[56:57], v[8:11], off offset:2048 nt
	global_store_dwordx4 v[56:57], v[12:15], off offset:2064 nt
	global_load_dwordx4 v[8:11], v[26:27], off
	s_nop 0
	global_load_dwordx4 v[12:15], v[26:27], off offset:16
	v_lshlrev_b32_e32 v48, 16, v4
	v_and_b32_e32 v49, 0xffff0000, v4
	v_lshlrev_b32_e32 v4, 16, v5
	v_and_b32_e32 v5, 0xffff0000, v5
	v_add_co_u32_e32 v46, vcc, s12, v34
	v_lshlrev_b32_e32 v50, 16, v6
	v_and_b32_e32 v51, 0xffff0000, v6
	v_lshlrev_b32_e32 v6, 16, v7
	v_and_b32_e32 v7, 0xffff0000, v7
	v_pk_mul_f32 v[52:53], v[36:37], v[4:5] op_sel_hi:[0,1]
	v_pk_mul_f32 v[4:5], v[36:37], v[48:49] op_sel_hi:[0,1]
	v_addc_co_u32_e32 v47, vcc, 0, v35, vcc
	v_pk_mul_f32 v[48:49], v[36:37], v[6:7] op_sel_hi:[0,1]
	v_pk_mul_f32 v[50:51], v[36:37], v[50:51] op_sel_hi:[0,1]
	v_lshl_add_u64 v[34:35], v[34:35], 0, s[8:9]
	s_waitcnt vmcnt(1)
	v_pk_mul_f32 v[4:5], v[4:5], v[8:9]
	v_pk_mul_f32 v[6:7], v[52:53], v[10:11]
	s_waitcnt vmcnt(0)
	v_pk_mul_f32 v[8:9], v[50:51], v[12:13]
	v_pk_mul_f32 v[10:11], v[48:49], v[14:15]
	global_store_dwordx4 v[46:47], v[4:7], off nt
	global_store_dwordx4 v[46:47], v[8:11], off offset:16 nt
	global_load_dwordx4 v[4:7], v[28:29], off
	s_nop 0
	global_load_dwordx4 v[8:11], v[28:29], off offset:16
	v_lshlrev_b32_e32 v12, 16, v0
	v_and_b32_e32 v13, 0xffff0000, v0
	v_lshlrev_b32_e32 v0, 16, v1
	v_and_b32_e32 v1, 0xffff0000, v1
	v_lshlrev_b32_e32 v14, 16, v2
	v_and_b32_e32 v15, 0xffff0000, v2
	v_lshlrev_b32_e32 v2, 16, v3
	v_and_b32_e32 v3, 0xffff0000, v3
	v_pk_mul_f32 v[48:49], v[36:37], v[0:1] op_sel_hi:[0,1]
	v_pk_mul_f32 v[0:1], v[36:37], v[12:13] op_sel_hi:[0,1]
	v_pk_mul_f32 v[12:13], v[36:37], v[2:3] op_sel_hi:[0,1]
	v_pk_mul_f32 v[14:15], v[36:37], v[14:15] op_sel_hi:[0,1]
	s_waitcnt vmcnt(1)
	v_pk_mul_f32 v[0:1], v[0:1], v[4:5]
	v_pk_mul_f32 v[2:3], v[48:49], v[6:7]
	s_waitcnt vmcnt(0)
	v_pk_mul_f32 v[4:5], v[14:15], v[8:9]
	v_pk_mul_f32 v[6:7], v[12:13], v[10:11]
	global_store_dwordx4 v[46:47], v[0:3], off offset:2048 nt
	global_store_dwordx4 v[46:47], v[4:7], off offset:2064 nt
	s_cbranch_scc1 .LBB0_1852
	v_readlane_b32 s47, v254, 60
	v_readlane_b32 s93, v254, 61

.LBB0_1910:
	v_lshl_add_u64 v[2:3], s[34:35], 0, v[30:31]
	global_load_dwordx4 v[46:49], v[16:17], off offset:16
	global_load_dwordx4 v[50:53], v[16:17], off
	global_load_dword v36, v[2:3], off
	v_lshl_add_u64 v[0:1], s[34:35], 0, v[32:33]
	v_add_co_u32_e32 v70, vcc, 0x30c00000, v0
	s_add_i32 s2, s2, s94
	s_nop 0
	v_addc_co_u32_e32 v71, vcc, 0, v1, vcc
	global_load_dwordx4 v[54:57], v[70:71], off
	global_load_dwordx4 v[58:61], v[70:71], off offset:1024
	global_load_dwordx4 v[62:65], v[70:71], off offset:2048
	v_add_co_u32_e32 v72, vcc, s3, v0
	v_lshl_add_u64 v[30:31], v[30:31], 0, s[4:5]
	s_nop 0
	v_addc_co_u32_e32 v73, vcc, 0, v1, vcc
	global_load_dwordx4 v[66:69], v[70:71], off offset:3072
	global_load_dwordx4 v[12:15], v[72:73], off
	global_load_dwordx4 v[8:11], v[72:73], off offset:1024
	global_load_dwordx4 v[4:7], v[72:73], off offset:2048
	global_load_dwordx4 v[0:3], v[72:73], off offset:3072
	v_lshl_add_u64 v[32:33], v[32:33], 0, s[6:7]
	s_cmpk_lt_i32 s2, 0x2200
	s_waitcnt vmcnt(8)
	ds_bpermute_b32 v45, v37, v36
	s_waitcnt vmcnt(7)
	v_lshlrev_b32_e32 v70, 16, v54
	s_waitcnt lgkmcnt(0)
	v_add_f32_e32 v36, v36, v45
	ds_bpermute_b32 v45, v38, v36
	v_and_b32_e32 v71, 0xffff0000, v54
	v_lshlrev_b32_e32 v54, 16, v55
	v_and_b32_e32 v55, 0xffff0000, v55
	v_lshlrev_b32_e32 v72, 16, v56
	s_waitcnt lgkmcnt(0)
	v_add_f32_e32 v36, v36, v45
	ds_bpermute_b32 v45, v39, v36
	v_and_b32_e32 v73, 0xffff0000, v56
	v_lshlrev_b32_e32 v56, 16, v57
	v_and_b32_e32 v57, 0xffff0000, v57
	s_waitcnt lgkmcnt(0)
	v_add_f32_e32 v36, v36, v45
	ds_bpermute_b32 v45, v40, v36
	s_waitcnt lgkmcnt(0)
	v_add_f32_e32 v36, v36, v45
	ds_bpermute_b32 v45, v41, v36
	s_waitcnt lgkmcnt(0)
	v_add_f32_e32 v36, v36, v45
	ds_bpermute_b32 v45, v42, v36
	s_waitcnt lgkmcnt(0)
	v_add_f32_e32 v36, v36, v45
	v_fmamk_f32 v36, v36, 0x39800000, v43
	v_mul_f32_e32 v45, 0x4f800000, v36
	v_cmp_gt_f32_e32 vcc, s13, v36
	s_nop 1
	v_cndmask_b32_e32 v36, v36, v45, vcc
	v_sqrt_f32_e32 v45, v36
	s_nop 0
	v_add_u32_e32 v74, -1, v45
	v_add_u32_e32 v75, 1, v45
	v_fma_f32 v76, -v74, v45, v36
	v_fma_f32 v77, -v75, v45, v36
	v_cmp_ge_f32_e64 s[0:1], 0, v76
	s_nop 1
	v_cndmask_b32_e64 v45, v45, v74, s[0:1]
	v_cmp_lt_f32_e64 s[0:1], 0, v77
	s_nop 1
	v_cndmask_b32_e64 v45, v45, v75, s[0:1]
	v_mul_f32_e32 v74, 0x37800000, v45
	v_cndmask_b32_e32 v45, v45, v74, vcc
	v_cmp_class_f32_e32 vcc, v36, v44
	s_nop 1
	v_cndmask_b32_e32 v36, v45, v36, vcc
	v_div_scale_f32 v45, s[0:1], v36, v36, 1.0
	v_rcp_f32_e32 v75, v45
	v_div_scale_f32 v74, vcc, 1.0, v36, 1.0
	v_fma_f32 v76, -v45, v75, 1.0
	v_fmac_f32_e32 v75, v76, v75
	v_mul_f32_e32 v76, v74, v75
	v_fma_f32 v77, -v45, v76, v74
	v_fmac_f32_e32 v76, v77, v75
	v_fma_f32 v45, -v45, v76, v74
	v_div_fmas_f32 v45, v45, v75, v76
	v_div_fixup_f32 v36, v45, v36, 1.0
	v_pk_mul_f32 v[70:71], v[36:37], v[70:71] op_sel_hi:[0,1]
	v_pk_mul_f32 v[54:55], v[36:37], v[54:55] op_sel_hi:[0,1]
	v_pk_mul_f32 v[72:73], v[36:37], v[72:73] op_sel_hi:[0,1]
	v_pk_mul_f32 v[56:57], v[36:37], v[56:57] op_sel_hi:[0,1]
	v_pk_mul_f32 v[52:53], v[52:53], v[54:55]
	v_pk_mul_f32 v[50:51], v[50:51], v[70:71]
	v_pk_mul_f32 v[48:49], v[48:49], v[56:57]
	v_pk_mul_f32 v[46:47], v[46:47], v[72:73]
	global_store_dwordx4 v[34:35], v[50:53], off nt
	global_store_dwordx4 v[34:35], v[46:49], off offset:16 nt
	global_load_dwordx4 v[46:49], v[16:17], off offset:2048
	s_nop 0
	global_load_dwordx4 v[50:53], v[16:17], off offset:2064
	s_waitcnt vmcnt(10)
	v_lshlrev_b32_e32 v54, 16, v58
	v_and_b32_e32 v55, 0xffff0000, v58
	v_lshlrev_b32_e32 v56, 16, v59
	v_and_b32_e32 v57, 0xffff0000, v59
	v_lshlrev_b32_e32 v58, 16, v60
	v_and_b32_e32 v59, 0xffff0000, v60
	v_lshlrev_b32_e32 v60, 16, v61
	v_and_b32_e32 v61, 0xffff0000, v61
	v_pk_mul_f32 v[56:57], v[36:37], v[56:57] op_sel_hi:[0,1]
	v_pk_mul_f32 v[54:55], v[36:37], v[54:55] op_sel_hi:[0,1]
	v_pk_mul_f32 v[60:61], v[36:37], v[60:61] op_sel_hi:[0,1]
	v_pk_mul_f32 v[58:59], v[36:37], v[58:59] op_sel_hi:[0,1]
	s_waitcnt vmcnt(1)
	v_pk_mul_f32 v[46:47], v[46:47], v[54:55]
	v_pk_mul_f32 v[48:49], v[48:49], v[56:57]
	s_waitcnt vmcnt(0)
	v_pk_mul_f32 v[50:51], v[50:51], v[58:59]
	v_pk_mul_f32 v[52:53], v[52:53], v[60:61]
	global_store_dwordx4 v[34:35], v[46:49], off offset:2048 nt
	global_store_dwordx4 v[34:35], v[50:53], off offset:2064 nt
	global_load_dwordx4 v[46:49], v[18:19], off
	s_nop 0
	global_load_dwordx4 v[50:53], v[18:19], off offset:16
	v_add_co_u32_e32 v54, vcc, s11, v34
	v_lshlrev_b32_e32 v58, 16, v62
	s_nop 0
	v_addc_co_u32_e32 v55, vcc, 0, v35, vcc
	v_and_b32_e32 v59, 0xffff0000, v62
	v_lshlrev_b32_e32 v60, 16, v63
	v_and_b32_e32 v61, 0xffff0000, v63
	v_add_co_u32_e32 v56, vcc, s10, v34
	v_lshlrev_b32_e32 v62, 16, v64
	v_and_b32_e32 v63, 0xffff0000, v64
	v_lshlrev_b32_e32 v64, 16, v65
	v_and_b32_e32 v65, 0xffff0000, v65
	v_pk_mul_f32 v[60:61], v[36:37], v[60:61] op_sel_hi:[0,1]
	v_pk_mul_f32 v[58:59], v[36:37], v[58:59] op_sel_hi:[0,1]
	v_addc_co_u32_e32 v57, vcc, 0, v35, vcc
	v_pk_mul_f32 v[64:65], v[36:37], v[64:65] op_sel_hi:[0,1]
	v_pk_mul_f32 v[62:63], v[36:37], v[62:63] op_sel_hi:[0,1]
	s_waitcnt vmcnt(1)
	v_pk_mul_f32 v[46:47], v[58:59], v[46:47]
	v_pk_mul_f32 v[48:49], v[60:61], v[48:49]
	s_waitcnt vmcnt(0)
	v_pk_mul_f32 v[50:51], v[62:63], v[50:51]
	v_pk_mul_f32 v[52:53], v[64:65], v[52:53]
	global_store_dwordx4 v[56:57], v[46:49], off offset:-4096 nt
	global_store_dwordx4 v[54:55], v[50:53], off offset:16 nt
	global_load_dwordx4 v[46:49], v[20:21], off
	s_nop 0
	global_load_dwordx4 v[50:53], v[20:21], off offset:16
	v_lshlrev_b32_e32 v58, 16, v66
	v_and_b32_e32 v59, 0xffff0000, v66
	v_lshlrev_b32_e32 v60, 16, v67
	v_and_b32_e32 v61, 0xffff0000, v67
	v_lshlrev_b32_e32 v62, 16, v68
	v_and_b32_e32 v63, 0xffff0000, v68
	v_lshlrev_b32_e32 v64, 16, v69
	v_and_b32_e32 v65, 0xffff0000, v69
	v_pk_mul_f32 v[60:61], v[36:37], v[60:61] op_sel_hi:[0,1]
	v_pk_mul_f32 v[58:59], v[36:37], v[58:59] op_sel_hi:[0,1]
	v_pk_mul_f32 v[64:65], v[36:37], v[64:65] op_sel_hi:[0,1]
	v_pk_mul_f32 v[62:63], v[36:37], v[62:63] op_sel_hi:[0,1]
	s_waitcnt vmcnt(1)
	v_pk_mul_f32 v[46:47], v[58:59], v[46:47]
	v_pk_mul_f32 v[48:49], v[60:61], v[48:49]
	s_waitcnt vmcnt(0)
	v_pk_mul_f32 v[50:51], v[62:63], v[50:51]
	v_pk_mul_f32 v[52:53], v[64:65], v[52:53]
	global_store_dwordx4 v[54:55], v[46:49], off offset:2048 nt
	global_store_dwordx4 v[54:55], v[50:53], off offset:2064 nt
	global_load_dwordx4 v[46:49], v[22:23], off
	s_nop 0
	global_load_dwordx4 v[50:53], v[22:23], off offset:16
	v_lshlrev_b32_e32 v54, 16, v12
	v_and_b32_e32 v55, 0xffff0000, v12
	v_lshlrev_b32_e32 v12, 16, v13
	v_and_b32_e32 v13, 0xffff0000, v13
	v_lshlrev_b32_e32 v58, 16, v14
	v_and_b32_e32 v59, 0xffff0000, v14
	v_lshlrev_b32_e32 v14, 16, v15
	v_and_b32_e32 v15, 0xffff0000, v15
	v_pk_mul_f32 v[60:61], v[36:37], v[12:13] op_sel_hi:[0,1]
	v_pk_mul_f32 v[12:13], v[36:37], v[54:55] op_sel_hi:[0,1]
	v_pk_mul_f32 v[54:55], v[36:37], v[14:15] op_sel_hi:[0,1]
	v_pk_mul_f32 v[58:59], v[36:37], v[58:59] op_sel_hi:[0,1]
	s_waitcnt vmcnt(1)
	v_pk_mul_f32 v[12:13], v[12:13], v[46:47]
	v_pk_mul_f32 v[14:15], v[60:61], v[48:49]
	s_waitcnt vmcnt(0)
	v_pk_mul_f32 v[46:47], v[58:59], v[50:51]
	v_pk_mul_f32 v[48:49], v[54:55], v[52:53]
	global_store_dwordx4 v[56:57], v[12:15], off nt
	global_store_dwordx4 v[56:57], v[46:49], off offset:16 nt
	global_load_dwordx4 v[12:15], v[24:25], off
	s_nop 0
	global_load_dwordx4 v[46:49], v[24:25], off offset:16
	v_lshlrev_b32_e32 v50, 16, v8
	v_and_b32_e32 v51, 0xffff0000, v8
	v_lshlrev_b32_e32 v8, 16, v9
	v_and_b32_e32 v9, 0xffff0000, v9
	v_lshlrev_b32_e32 v52, 16, v10
	v_and_b32_e32 v53, 0xffff0000, v10
	v_lshlrev_b32_e32 v10, 16, v11
	v_and_b32_e32 v11, 0xffff0000, v11
	v_pk_mul_f32 v[54:55], v[36:37], v[8:9] op_sel_hi:[0,1]
	v_pk_mul_f32 v[8:9], v[36:37], v[50:51] op_sel_hi:[0,1]
	v_pk_mul_f32 v[50:51], v[36:37], v[10:11] op_sel_hi:[0,1]
	v_pk_mul_f32 v[52:53], v[36:37], v[52:53] op_sel_hi:[0,1]
	s_waitcnt vmcnt(1)
	v_pk_mul_f32 v[8:9], v[8:9], v[12:13]
	v_pk_mul_f32 v[10:11], v[54:55], v[14:15]
	s_waitcnt vmcnt(0)
	v_pk_mul_f32 v[12:13], v[52:53], v[46:47]
	v_pk_mul_f32 v[14:15], v[50:51], v[48:49]
	global_store_dwordx4 v[56:57], v[8:11], off offset:2048 nt
	global_store_dwordx4 v[56:57], v[12:15], off offset:2064 nt
	global_load_dwordx4 v[8:11], v[26:27], off
	s_nop 0
	global_load_dwordx4 v[12:15], v[26:27], off offset:16
	v_lshlrev_b32_e32 v48, 16, v4
	v_and_b32_e32 v49, 0xffff0000, v4
	v_lshlrev_b32_e32 v4, 16, v5
	v_and_b32_e32 v5, 0xffff0000, v5
	v_add_co_u32_e32 v46, vcc, s12, v34
	v_lshlrev_b32_e32 v50, 16, v6
	v_and_b32_e32 v51, 0xffff0000, v6
	v_lshlrev_b32_e32 v6, 16, v7
	v_and_b32_e32 v7, 0xffff0000, v7
	v_pk_mul_f32 v[52:53], v[36:37], v[4:5] op_sel_hi:[0,1]
	v_pk_mul_f32 v[4:5], v[36:37], v[48:49] op_sel_hi:[0,1]
	v_addc_co_u32_e32 v47, vcc, 0, v35, vcc
	v_pk_mul_f32 v[48:49], v[36:37], v[6:7] op_sel_hi:[0,1]
	v_pk_mul_f32 v[50:51], v[36:37], v[50:51] op_sel_hi:[0,1]
	v_lshl_add_u64 v[34:35], v[34:35], 0, s[8:9]
	s_waitcnt vmcnt(1)
	v_pk_mul_f32 v[4:5], v[4:5], v[8:9]
	v_pk_mul_f32 v[6:7], v[52:53], v[10:11]
	s_waitcnt vmcnt(0)
	v_pk_mul_f32 v[8:9], v[50:51], v[12:13]
	v_pk_mul_f32 v[10:11], v[48:49], v[14:15]
	global_store_dwordx4 v[46:47], v[4:7], off nt
	global_store_dwordx4 v[46:47], v[8:11], off offset:16 nt
	global_load_dwordx4 v[4:7], v[28:29], off
	s_nop 0
	global_load_dwordx4 v[8:11], v[28:29], off offset:16
	v_lshlrev_b32_e32 v12, 16, v0
	v_and_b32_e32 v13, 0xffff0000, v0
	v_lshlrev_b32_e32 v0, 16, v1
	v_and_b32_e32 v1, 0xffff0000, v1
	v_lshlrev_b32_e32 v14, 16, v2
	v_and_b32_e32 v15, 0xffff0000, v2
	v_lshlrev_b32_e32 v2, 16, v3
	v_and_b32_e32 v3, 0xffff0000, v3
	v_pk_mul_f32 v[48:49], v[36:37], v[0:1] op_sel_hi:[0,1]
	v_pk_mul_f32 v[0:1], v[36:37], v[12:13] op_sel_hi:[0,1]
	v_pk_mul_f32 v[12:13], v[36:37], v[2:3] op_sel_hi:[0,1]
	v_pk_mul_f32 v[14:15], v[36:37], v[14:15] op_sel_hi:[0,1]
	s_waitcnt vmcnt(1)
	v_pk_mul_f32 v[0:1], v[0:1], v[4:5]
	v_pk_mul_f32 v[2:3], v[48:49], v[6:7]
	s_waitcnt vmcnt(0)
	v_pk_mul_f32 v[4:5], v[14:15], v[8:9]
	v_pk_mul_f32 v[6:7], v[12:13], v[10:11]
	global_store_dwordx4 v[46:47], v[0:3], off offset:2048 nt
	global_store_dwordx4 v[46:47], v[4:7], off offset:2064 nt
	s_cbranch_scc1 .LBB0_1910
